# v13 + removed the vmcnt(0) flush in the tile-loop preheader of 7 GEMM phases (the in-loop counted waits already cover the needed loads)
# baseline (speedup 1.0000x reference)
.LBB0_515:
	s_ashr_i32 s23, s22, 31
	s_lshl_b64 s[26:27], s[22:23], 20
	s_add_u32 s26, s0, s26
	s_addc_u32 s27, s1, s27
	s_and_b64 s[28:29], s[4:5], exec
	s_cselect_b32 s7, s27, s9
	s_cselect_b32 s23, s26, s8
	s_ashr_i32 s21, s20, 31
	s_lshl_b64 s[28:29], s[20:21], 20
	s_add_u32 s28, s2, s28
	s_addc_u32 s29, s3, s29
	s_and_b64 s[36:37], s[4:5], exec
	s_cselect_b32 s21, s29, s35
	s_cselect_b32 s31, s28, s34
	s_add_u32 s8, s8, 0x80080
	s_addc_u32 s9, s9, 0
	s_add_u32 s52, s34, 0x100
	v_mov_b32_e32 v0, 0
	s_addc_u32 s53, s35, 0
	s_mov_b32 s54, -2
	v_mov_b32_e32 v1, v0
	v_mov_b32_e32 v2, v0
	v_mov_b32_e32 v3, v0
	v_mov_b32_e32 v4, v0
	s_waitcnt lgkmcnt(0)
	v_mov_b32_e32 v5, v0
	v_mov_b32_e32 v6, v0
	v_mov_b32_e32 v7, v0
	v_mov_b32_e32 v16, v0
	v_mov_b32_e32 v17, v0
	v_mov_b32_e32 v18, v0
	v_mov_b32_e32 v19, v0
	v_mov_b32_e32 v20, v0
	v_mov_b32_e32 v21, v0
	v_mov_b32_e32 v22, v0
	v_mov_b32_e32 v23, v0
	v_mov_b32_e32 v32, v0
	v_mov_b32_e32 v33, v0
	v_mov_b32_e32 v34, v0
	v_mov_b32_e32 v35, v0
	v_mov_b32_e32 v36, v0
	v_mov_b32_e32 v37, v0
	v_mov_b32_e32 v38, v0
	v_mov_b32_e32 v39, v0
	v_mov_b32_e32 v48, v0
	v_mov_b32_e32 v49, v0
	v_mov_b32_e32 v50, v0
	v_mov_b32_e32 v51, v0
	v_mov_b32_e32 v52, v0
	v_mov_b32_e32 v53, v0
	v_mov_b32_e32 v54, v0
	v_mov_b32_e32 v55, v0
	v_mov_b32_e32 v8, v0
	v_mov_b32_e32 v9, v0
	v_mov_b32_e32 v10, v0
	v_mov_b32_e32 v11, v0
	v_mov_b32_e32 v12, v0
	v_mov_b32_e32 v13, v0
	v_mov_b32_e32 v14, v0
	v_mov_b32_e32 v15, v0
	v_mov_b32_e32 v24, v0
	v_mov_b32_e32 v25, v0
	v_mov_b32_e32 v26, v0
	v_mov_b32_e32 v27, v0
	v_mov_b32_e32 v28, v0
	v_mov_b32_e32 v29, v0
	v_mov_b32_e32 v30, v0
	v_mov_b32_e32 v31, v0
	v_mov_b32_e32 v40, v0
	v_mov_b32_e32 v41, v0
	v_mov_b32_e32 v42, v0
	v_mov_b32_e32 v43, v0
	v_mov_b32_e32 v44, v0
	v_mov_b32_e32 v45, v0
	v_mov_b32_e32 v46, v0
	v_mov_b32_e32 v47, v0
	v_mov_b32_e32 v56, v0
	v_mov_b32_e32 v57, v0
	v_mov_b32_e32 v58, v0
	v_mov_b32_e32 v59, v0
	v_mov_b32_e32 v60, v0
	v_mov_b32_e32 v61, v0
	v_mov_b32_e32 v62, v0
	v_mov_b32_e32 v63, v0
	v_mov_b32_e32 v64, v0
	v_mov_b32_e32 v65, v0
	v_mov_b32_e32 v66, v0
	v_mov_b32_e32 v67, v0
	v_mov_b32_e32 v68, v0
	v_mov_b32_e32 v69, v0
	v_mov_b32_e32 v70, v0
	v_mov_b32_e32 v71, v0
	v_mov_b32_e32 v80, v0
	v_mov_b32_e32 v81, v0
	v_mov_b32_e32 v82, v0
	v_mov_b32_e32 v83, v0
	v_mov_b32_e32 v84, v0
	v_mov_b32_e32 v85, v0
	v_mov_b32_e32 v86, v0
	v_mov_b32_e32 v87, v0
	v_mov_b32_e32 v96, v0
	v_mov_b32_e32 v97, v0
	v_mov_b32_e32 v98, v0
	v_mov_b32_e32 v99, v0
	v_mov_b32_e32 v100, v0
	v_mov_b32_e32 v101, v0
	v_mov_b32_e32 v102, v0
	v_mov_b32_e32 v103, v0
	v_mov_b32_e32 v112, v0
	v_mov_b32_e32 v113, v0
	v_mov_b32_e32 v114, v0
	v_mov_b32_e32 v115, v0
	v_mov_b32_e32 v116, v0
	v_mov_b32_e32 v117, v0
	v_mov_b32_e32 v118, v0
	v_mov_b32_e32 v119, v0
	v_mov_b32_e32 v72, v0
	v_mov_b32_e32 v73, v0
	v_mov_b32_e32 v74, v0
	v_mov_b32_e32 v75, v0
	v_mov_b32_e32 v76, v0
	v_mov_b32_e32 v77, v0
	v_mov_b32_e32 v78, v0
	v_mov_b32_e32 v79, v0
	v_mov_b32_e32 v88, v0
	v_mov_b32_e32 v89, v0
	v_mov_b32_e32 v90, v0
	v_mov_b32_e32 v91, v0
	v_mov_b32_e32 v92, v0
	v_mov_b32_e32 v93, v0
	v_mov_b32_e32 v94, v0
	v_mov_b32_e32 v95, v0
	v_mov_b32_e32 v104, v0
	v_mov_b32_e32 v105, v0
	v_mov_b32_e32 v106, v0
	v_mov_b32_e32 v107, v0
	v_mov_b32_e32 v108, v0
	v_mov_b32_e32 v109, v0
	v_mov_b32_e32 v110, v0
	v_mov_b32_e32 v111, v0
	v_mov_b32_e32 v124, v0
	v_mov_b32_e32 v125, v0
	v_mov_b32_e32 v126, v0
	v_mov_b32_e32 v127, v0
	v_mov_b32_e32 v128, v0
	v_mov_b32_e32 v129, v0
	v_mov_b32_e32 v130, v0
	v_mov_b32_e32 v131, v0

.LBB0_631:
	s_ashr_i32 s17, s16, 31
	s_lshl_b64 s[18:19], s[16:17], 20
	s_add_u32 s18, s72, s18
	s_addc_u32 s19, s73, s19
	s_and_b64 s[20:21], s[4:5], exec
	s_cselect_b32 s17, s19, s7
	s_cselect_b32 s46, s18, s6
	s_ashr_i32 s15, s14, 31
	s_lshl_b64 s[20:21], s[14:15], 20
	s_add_u32 s20, s2, s20
	s_addc_u32 s21, s3, s21
	s_and_b64 s[26:27], s[4:5], exec
	s_cselect_b32 s15, s21, s23
	s_cselect_b32 s47, s20, s22
	s_add_u32 s6, s6, 0x80080
	s_addc_u32 s7, s7, 0
	s_add_u32 s48, s22, 0x100
	v_mov_b32_e32 v0, 0
	s_addc_u32 s49, s23, 0
	s_mov_b32 s50, -2
	v_mov_b32_e32 v1, v0
	v_mov_b32_e32 v2, v0
	v_mov_b32_e32 v3, v0
	v_mov_b32_e32 v8, v0
	v_mov_b32_e32 v9, v0
	v_mov_b32_e32 v10, v0
	v_mov_b32_e32 v11, v0
	v_mov_b32_e32 v16, v0
	v_mov_b32_e32 v17, v0
	v_mov_b32_e32 v18, v0
	v_mov_b32_e32 v19, v0
	v_mov_b32_e32 v24, v0
	v_mov_b32_e32 v25, v0
	v_mov_b32_e32 v26, v0
	v_mov_b32_e32 v27, v0
	v_mov_b32_e32 v32, v0
	v_mov_b32_e32 v33, v0
	v_mov_b32_e32 v34, v0
	v_mov_b32_e32 v35, v0
	v_mov_b32_e32 v40, v0
	v_mov_b32_e32 v41, v0
	v_mov_b32_e32 v42, v0
	v_mov_b32_e32 v43, v0
	v_mov_b32_e32 v48, v0
	v_mov_b32_e32 v49, v0
	v_mov_b32_e32 v50, v0
	v_mov_b32_e32 v51, v0
	v_mov_b32_e32 v56, v0
	v_mov_b32_e32 v57, v0
	v_mov_b32_e32 v58, v0
	v_mov_b32_e32 v59, v0
	v_mov_b32_e32 v4, v0
	v_mov_b32_e32 v5, v0
	v_mov_b32_e32 v6, v0
	v_mov_b32_e32 v7, v0
	v_mov_b32_e32 v12, v0
	v_mov_b32_e32 v13, v0
	v_mov_b32_e32 v14, v0
	v_mov_b32_e32 v15, v0
	v_mov_b32_e32 v20, v0
	v_mov_b32_e32 v21, v0
	v_mov_b32_e32 v22, v0
	v_mov_b32_e32 v23, v0
	v_mov_b32_e32 v28, v0
	v_mov_b32_e32 v29, v0
	v_mov_b32_e32 v30, v0
	v_mov_b32_e32 v31, v0
	v_mov_b32_e32 v36, v0
	v_mov_b32_e32 v37, v0
	v_mov_b32_e32 v38, v0
	v_mov_b32_e32 v39, v0
	v_mov_b32_e32 v44, v0
	v_mov_b32_e32 v45, v0
	v_mov_b32_e32 v46, v0
	v_mov_b32_e32 v47, v0
	v_mov_b32_e32 v52, v0
	v_mov_b32_e32 v53, v0
	v_mov_b32_e32 v54, v0
	v_mov_b32_e32 v55, v0
	v_mov_b32_e32 v60, v0
	v_mov_b32_e32 v61, v0
	v_mov_b32_e32 v62, v0
	v_mov_b32_e32 v63, v0
	v_mov_b32_e32 v64, v0
	v_mov_b32_e32 v65, v0
	v_mov_b32_e32 v66, v0
	v_mov_b32_e32 v67, v0
	v_mov_b32_e32 v72, v0
	v_mov_b32_e32 v73, v0
	v_mov_b32_e32 v74, v0
	v_mov_b32_e32 v75, v0
	v_mov_b32_e32 v80, v0
	v_mov_b32_e32 v81, v0
	v_mov_b32_e32 v82, v0
	v_mov_b32_e32 v83, v0
	v_mov_b32_e32 v88, v0
	v_mov_b32_e32 v89, v0
	v_mov_b32_e32 v90, v0
	v_mov_b32_e32 v91, v0
	v_mov_b32_e32 v96, v0
	v_mov_b32_e32 v97, v0
	v_mov_b32_e32 v98, v0
	v_mov_b32_e32 v99, v0
	v_mov_b32_e32 v104, v0
	v_mov_b32_e32 v105, v0
	v_mov_b32_e32 v106, v0
	v_mov_b32_e32 v107, v0
	v_mov_b32_e32 v112, v0
	v_mov_b32_e32 v113, v0
	v_mov_b32_e32 v114, v0
	v_mov_b32_e32 v115, v0
	v_mov_b32_e32 v120, v0
	v_mov_b32_e32 v121, v0
	v_mov_b32_e32 v122, v0
	v_mov_b32_e32 v123, v0
	v_mov_b32_e32 v68, v0
	v_mov_b32_e32 v69, v0
	v_mov_b32_e32 v70, v0
	v_mov_b32_e32 v71, v0
	v_mov_b32_e32 v76, v0
	v_mov_b32_e32 v77, v0
	v_mov_b32_e32 v78, v0
	v_mov_b32_e32 v79, v0
	v_mov_b32_e32 v84, v0
	v_mov_b32_e32 v85, v0
	v_mov_b32_e32 v86, v0
	v_mov_b32_e32 v87, v0
	v_mov_b32_e32 v92, v0
	v_mov_b32_e32 v93, v0
	v_mov_b32_e32 v94, v0
	v_mov_b32_e32 v95, v0
	v_mov_b32_e32 v100, v0
	v_mov_b32_e32 v101, v0
	v_mov_b32_e32 v102, v0
	v_mov_b32_e32 v103, v0
	v_mov_b32_e32 v108, v0
	v_mov_b32_e32 v109, v0
	v_mov_b32_e32 v110, v0
	v_mov_b32_e32 v111, v0
	v_mov_b32_e32 v116, v0
	v_mov_b32_e32 v117, v0
	v_mov_b32_e32 v118, v0
	v_mov_b32_e32 v119, v0
	v_mov_b32_e32 v124, v0
	v_mov_b32_e32 v125, v0
	v_mov_b32_e32 v126, v0
	v_mov_b32_e32 v127, v0

.LBB0_713:
	s_add_u32 s44, s18, 0x100
	v_mov_b32_e32 v0, 0
	s_addc_u32 s45, s19, 0
	s_mov_b32 s46, -2
	s_waitcnt lgkmcnt(0)
	v_mov_b32_e32 v1, v0
	v_mov_b32_e32 v2, v0
	v_mov_b32_e32 v3, v0
	v_mov_b32_e32 v4, v0
	v_mov_b32_e32 v5, v0
	v_mov_b32_e32 v6, v0
	v_mov_b32_e32 v7, v0
	v_mov_b32_e32 v16, v0
	v_mov_b32_e32 v17, v0
	v_mov_b32_e32 v18, v0
	v_mov_b32_e32 v19, v0
	v_mov_b32_e32 v20, v0
	v_mov_b32_e32 v21, v0
	v_mov_b32_e32 v22, v0
	v_mov_b32_e32 v23, v0
	v_mov_b32_e32 v32, v0
	v_mov_b32_e32 v33, v0
	v_mov_b32_e32 v34, v0
	v_mov_b32_e32 v35, v0
	v_mov_b32_e32 v36, v0
	v_mov_b32_e32 v37, v0
	v_mov_b32_e32 v38, v0
	v_mov_b32_e32 v39, v0
	v_mov_b32_e32 v48, v0
	v_mov_b32_e32 v49, v0
	v_mov_b32_e32 v50, v0
	v_mov_b32_e32 v51, v0
	v_mov_b32_e32 v52, v0
	v_mov_b32_e32 v53, v0
	v_mov_b32_e32 v54, v0
	v_mov_b32_e32 v55, v0
	v_mov_b32_e32 v8, v0
	v_mov_b32_e32 v9, v0
	v_mov_b32_e32 v10, v0
	v_mov_b32_e32 v11, v0
	v_mov_b32_e32 v12, v0
	v_mov_b32_e32 v13, v0
	v_mov_b32_e32 v14, v0
	v_mov_b32_e32 v15, v0
	v_mov_b32_e32 v24, v0
	v_mov_b32_e32 v25, v0
	v_mov_b32_e32 v26, v0
	v_mov_b32_e32 v27, v0
	v_mov_b32_e32 v28, v0
	v_mov_b32_e32 v29, v0
	v_mov_b32_e32 v30, v0
	v_mov_b32_e32 v31, v0
	v_mov_b32_e32 v40, v0
	v_mov_b32_e32 v41, v0
	v_mov_b32_e32 v42, v0
	v_mov_b32_e32 v43, v0
	v_mov_b32_e32 v44, v0
	v_mov_b32_e32 v45, v0
	v_mov_b32_e32 v46, v0
	v_mov_b32_e32 v47, v0
	v_mov_b32_e32 v56, v0
	v_mov_b32_e32 v57, v0
	v_mov_b32_e32 v58, v0
	v_mov_b32_e32 v59, v0
	v_mov_b32_e32 v60, v0
	v_mov_b32_e32 v61, v0
	v_mov_b32_e32 v62, v0
	v_mov_b32_e32 v63, v0
	v_mov_b32_e32 v64, v0
	v_mov_b32_e32 v65, v0
	v_mov_b32_e32 v66, v0
	v_mov_b32_e32 v67, v0
	v_mov_b32_e32 v68, v0
	v_mov_b32_e32 v69, v0
	v_mov_b32_e32 v70, v0
	v_mov_b32_e32 v71, v0
	v_mov_b32_e32 v80, v0
	v_mov_b32_e32 v81, v0
	v_mov_b32_e32 v82, v0
	v_mov_b32_e32 v83, v0
	v_mov_b32_e32 v84, v0
	v_mov_b32_e32 v85, v0
	v_mov_b32_e32 v86, v0
	v_mov_b32_e32 v87, v0
	v_mov_b32_e32 v96, v0
	v_mov_b32_e32 v97, v0
	v_mov_b32_e32 v98, v0
	v_mov_b32_e32 v99, v0
	v_mov_b32_e32 v100, v0
	v_mov_b32_e32 v101, v0
	v_mov_b32_e32 v102, v0
	v_mov_b32_e32 v103, v0
	v_mov_b32_e32 v112, v0
	v_mov_b32_e32 v113, v0
	v_mov_b32_e32 v114, v0
	v_mov_b32_e32 v115, v0
	v_mov_b32_e32 v116, v0
	v_mov_b32_e32 v117, v0
	v_mov_b32_e32 v118, v0
	v_mov_b32_e32 v119, v0
	v_mov_b32_e32 v72, v0
	v_mov_b32_e32 v73, v0
	v_mov_b32_e32 v74, v0
	v_mov_b32_e32 v75, v0
	v_mov_b32_e32 v76, v0
	v_mov_b32_e32 v77, v0
	v_mov_b32_e32 v78, v0
	v_mov_b32_e32 v79, v0
	v_mov_b32_e32 v88, v0
	v_mov_b32_e32 v89, v0
	v_mov_b32_e32 v90, v0
	v_mov_b32_e32 v91, v0
	v_mov_b32_e32 v92, v0
	v_mov_b32_e32 v93, v0
	v_mov_b32_e32 v94, v0
	v_mov_b32_e32 v95, v0
	v_mov_b32_e32 v104, v0
	v_mov_b32_e32 v105, v0
	v_mov_b32_e32 v106, v0
	v_mov_b32_e32 v107, v0
	v_mov_b32_e32 v108, v0
	v_mov_b32_e32 v109, v0
	v_mov_b32_e32 v110, v0
	v_mov_b32_e32 v111, v0
	v_mov_b32_e32 v120, v0
	v_mov_b32_e32 v121, v0
	v_mov_b32_e32 v122, v0
	v_mov_b32_e32 v123, v0
	v_mov_b32_e32 v124, v0
	v_mov_b32_e32 v125, v0
	v_mov_b32_e32 v126, v0
	v_mov_b32_e32 v127, v0

.LBB0_799:
	s_ashr_i32 s17, s16, 31
	s_lshl_b64 s[18:19], s[16:17], 20
	s_add_u32 s18, s72, s18
	s_addc_u32 s19, s73, s19
	s_and_b64 s[20:21], s[4:5], exec
	s_cselect_b32 s1, s19, s27
	s_cselect_b32 s17, s18, s26
	s_ashr_i32 s15, s14, 31
	s_lshl_b64 s[20:21], s[14:15], 20
	s_add_u32 s20, s3, s20
	s_addc_u32 s21, s25, s21
	s_and_b64 s[30:31], s[4:5], exec
	s_cselect_b32 s15, s21, s29
	s_cselect_b32 s50, s20, s28
	s_add_u32 s26, s26, 0x80080
	s_addc_u32 s27, s27, 0
	s_add_u32 s51, s28, 0x100
	v_mov_b32_e32 v0, 0
	s_addc_u32 s52, s29, 0
	s_mov_b32 s53, -2
	s_waitcnt lgkmcnt(0)
	v_mov_b32_e32 v1, v0
	v_mov_b32_e32 v2, v0
	v_mov_b32_e32 v3, v0
	v_mov_b32_e32 v4, v0
	v_mov_b32_e32 v5, v0
	v_mov_b32_e32 v6, v0
	v_mov_b32_e32 v7, v0
	v_mov_b32_e32 v16, v0
	v_mov_b32_e32 v17, v0
	v_mov_b32_e32 v18, v0
	v_mov_b32_e32 v19, v0
	v_mov_b32_e32 v20, v0
	v_mov_b32_e32 v21, v0
	v_mov_b32_e32 v22, v0
	v_mov_b32_e32 v23, v0
	v_mov_b32_e32 v32, v0
	v_mov_b32_e32 v33, v0
	v_mov_b32_e32 v34, v0
	v_mov_b32_e32 v35, v0
	v_mov_b32_e32 v36, v0
	v_mov_b32_e32 v37, v0
	v_mov_b32_e32 v38, v0
	v_mov_b32_e32 v39, v0
	v_mov_b32_e32 v48, v0
	v_mov_b32_e32 v49, v0
	v_mov_b32_e32 v50, v0
	v_mov_b32_e32 v51, v0
	v_mov_b32_e32 v52, v0
	v_mov_b32_e32 v53, v0
	v_mov_b32_e32 v54, v0
	v_mov_b32_e32 v55, v0
	v_mov_b32_e32 v8, v0
	v_mov_b32_e32 v9, v0
	v_mov_b32_e32 v10, v0
	v_mov_b32_e32 v11, v0
	v_mov_b32_e32 v12, v0
	v_mov_b32_e32 v13, v0
	v_mov_b32_e32 v14, v0
	v_mov_b32_e32 v15, v0
	v_mov_b32_e32 v24, v0
	v_mov_b32_e32 v25, v0
	v_mov_b32_e32 v26, v0
	v_mov_b32_e32 v27, v0
	v_mov_b32_e32 v28, v0
	v_mov_b32_e32 v29, v0
	v_mov_b32_e32 v30, v0
	v_mov_b32_e32 v31, v0
	v_mov_b32_e32 v40, v0
	v_mov_b32_e32 v41, v0
	v_mov_b32_e32 v42, v0
	v_mov_b32_e32 v43, v0
	v_mov_b32_e32 v44, v0
	v_mov_b32_e32 v45, v0
	v_mov_b32_e32 v46, v0
	v_mov_b32_e32 v47, v0
	v_mov_b32_e32 v56, v0
	v_mov_b32_e32 v57, v0
	v_mov_b32_e32 v58, v0
	v_mov_b32_e32 v59, v0
	v_mov_b32_e32 v60, v0
	v_mov_b32_e32 v61, v0
	v_mov_b32_e32 v62, v0
	v_mov_b32_e32 v63, v0
	v_mov_b32_e32 v64, v0
	v_mov_b32_e32 v65, v0
	v_mov_b32_e32 v66, v0
	v_mov_b32_e32 v67, v0
	v_mov_b32_e32 v68, v0
	v_mov_b32_e32 v69, v0
	v_mov_b32_e32 v70, v0
	v_mov_b32_e32 v71, v0
	v_mov_b32_e32 v80, v0
	v_mov_b32_e32 v81, v0
	v_mov_b32_e32 v82, v0
	v_mov_b32_e32 v83, v0
	v_mov_b32_e32 v84, v0
	v_mov_b32_e32 v85, v0
	v_mov_b32_e32 v86, v0
	v_mov_b32_e32 v87, v0
	v_mov_b32_e32 v96, v0
	v_mov_b32_e32 v97, v0
	v_mov_b32_e32 v98, v0
	v_mov_b32_e32 v99, v0
	v_mov_b32_e32 v100, v0
	v_mov_b32_e32 v101, v0
	v_mov_b32_e32 v102, v0
	v_mov_b32_e32 v103, v0
	v_mov_b32_e32 v112, v0
	v_mov_b32_e32 v113, v0
	v_mov_b32_e32 v114, v0
	v_mov_b32_e32 v115, v0
	v_mov_b32_e32 v116, v0
	v_mov_b32_e32 v117, v0
	v_mov_b32_e32 v118, v0
	v_mov_b32_e32 v119, v0
	v_mov_b32_e32 v72, v0
	v_mov_b32_e32 v73, v0
	v_mov_b32_e32 v74, v0
	v_mov_b32_e32 v75, v0
	v_mov_b32_e32 v76, v0
	v_mov_b32_e32 v77, v0
	v_mov_b32_e32 v78, v0
	v_mov_b32_e32 v79, v0
	v_mov_b32_e32 v88, v0
	v_mov_b32_e32 v89, v0
	v_mov_b32_e32 v90, v0
	v_mov_b32_e32 v91, v0
	v_mov_b32_e32 v92, v0
	v_mov_b32_e32 v93, v0
	v_mov_b32_e32 v94, v0
	v_mov_b32_e32 v95, v0
	v_mov_b32_e32 v104, v0
	v_mov_b32_e32 v105, v0
	v_mov_b32_e32 v106, v0
	v_mov_b32_e32 v107, v0
	v_mov_b32_e32 v108, v0
	v_mov_b32_e32 v109, v0
	v_mov_b32_e32 v110, v0
	v_mov_b32_e32 v111, v0
	v_mov_b32_e32 v120, v0
	v_mov_b32_e32 v121, v0
	v_mov_b32_e32 v122, v0
	v_mov_b32_e32 v123, v0
	v_mov_b32_e32 v124, v0
	v_mov_b32_e32 v125, v0
	v_mov_b32_e32 v126, v0
	v_mov_b32_e32 v127, v0

.LBB0_895:
	s_ashr_i32 s19, s18, 31
	s_lshl_b64 s[22:23], s[18:19], 18
	s_add_u32 s22, s2, s22
	s_addc_u32 s23, s3, s23
	s_and_b64 s[0:1], s[0:1], exec
	s_cselect_b32 s19, s23, s29
	s_cselect_b32 s27, s22, s28
	s_add_u32 s35, s28, 0x100
	v_mov_b32_e32 v0, 0
	s_addc_u32 s36, s29, 0
	s_mov_b32 s37, -2
	v_mov_b32_e32 v1, v0
	v_mov_b32_e32 v2, v0
	v_mov_b32_e32 v3, v0
	v_mov_b32_e32 v4, v0
	v_mov_b32_e32 v5, v0
	v_mov_b32_e32 v6, v0
	v_mov_b32_e32 v7, v0
	v_mov_b32_e32 v16, v0
	v_mov_b32_e32 v17, v0
	v_mov_b32_e32 v18, v0
	v_mov_b32_e32 v19, v0
	v_mov_b32_e32 v20, v0
	v_mov_b32_e32 v21, v0
	v_mov_b32_e32 v22, v0
	v_mov_b32_e32 v23, v0
	v_mov_b32_e32 v32, v0
	v_mov_b32_e32 v33, v0
	v_mov_b32_e32 v34, v0
	v_mov_b32_e32 v35, v0
	v_mov_b32_e32 v36, v0
	v_mov_b32_e32 v37, v0
	v_mov_b32_e32 v38, v0
	v_mov_b32_e32 v39, v0
	v_mov_b32_e32 v48, v0
	v_mov_b32_e32 v49, v0
	v_mov_b32_e32 v50, v0
	v_mov_b32_e32 v51, v0
	v_mov_b32_e32 v52, v0
	v_mov_b32_e32 v53, v0
	v_mov_b32_e32 v54, v0
	v_mov_b32_e32 v55, v0
	v_mov_b32_e32 v8, v0
	v_mov_b32_e32 v9, v0
	v_mov_b32_e32 v10, v0
	v_mov_b32_e32 v11, v0
	v_mov_b32_e32 v12, v0
	v_mov_b32_e32 v13, v0
	v_mov_b32_e32 v14, v0
	v_mov_b32_e32 v15, v0
	v_mov_b32_e32 v24, v0
	v_mov_b32_e32 v25, v0
	v_mov_b32_e32 v26, v0
	v_mov_b32_e32 v27, v0
	v_mov_b32_e32 v28, v0
	v_mov_b32_e32 v29, v0
	v_mov_b32_e32 v30, v0
	v_mov_b32_e32 v31, v0
	v_mov_b32_e32 v40, v0
	v_mov_b32_e32 v41, v0
	v_mov_b32_e32 v42, v0
	v_mov_b32_e32 v43, v0
	v_mov_b32_e32 v44, v0
	v_mov_b32_e32 v45, v0
	v_mov_b32_e32 v46, v0
	v_mov_b32_e32 v47, v0
	v_mov_b32_e32 v56, v0
	v_mov_b32_e32 v57, v0
	v_mov_b32_e32 v58, v0
	v_mov_b32_e32 v59, v0
	v_mov_b32_e32 v60, v0
	v_mov_b32_e32 v61, v0
	v_mov_b32_e32 v62, v0
	v_mov_b32_e32 v63, v0
	v_mov_b32_e32 v64, v0
	v_mov_b32_e32 v65, v0
	v_mov_b32_e32 v66, v0
	v_mov_b32_e32 v67, v0
	v_mov_b32_e32 v68, v0
	v_mov_b32_e32 v69, v0
	v_mov_b32_e32 v70, v0
	v_mov_b32_e32 v71, v0
	v_mov_b32_e32 v80, v0
	v_mov_b32_e32 v81, v0
	v_mov_b32_e32 v82, v0
	v_mov_b32_e32 v83, v0
	v_mov_b32_e32 v84, v0
	v_mov_b32_e32 v85, v0
	v_mov_b32_e32 v86, v0
	v_mov_b32_e32 v87, v0
	v_mov_b32_e32 v96, v0
	v_mov_b32_e32 v97, v0
	v_mov_b32_e32 v98, v0
	v_mov_b32_e32 v99, v0
	v_mov_b32_e32 v100, v0
	v_mov_b32_e32 v101, v0
	v_mov_b32_e32 v102, v0
	v_mov_b32_e32 v103, v0
	v_mov_b32_e32 v120, v0
	v_mov_b32_e32 v121, v0
	v_mov_b32_e32 v122, v0
	v_mov_b32_e32 v123, v0
	v_mov_b32_e32 v128, v0
	v_mov_b32_e32 v129, v0
	v_mov_b32_e32 v130, v0
	v_mov_b32_e32 v131, v0
	v_mov_b32_e32 v72, v0
	v_mov_b32_e32 v73, v0
	v_mov_b32_e32 v74, v0
	v_mov_b32_e32 v75, v0
	v_mov_b32_e32 v76, v0
	v_mov_b32_e32 v77, v0
	v_mov_b32_e32 v78, v0
	v_mov_b32_e32 v79, v0
	v_mov_b32_e32 v88, v0
	v_mov_b32_e32 v89, v0
	v_mov_b32_e32 v90, v0
	v_mov_b32_e32 v91, v0
	v_mov_b32_e32 v92, v0
	v_mov_b32_e32 v93, v0
	v_mov_b32_e32 v94, v0
	v_mov_b32_e32 v95, v0
	v_mov_b32_e32 v112, v0
	v_mov_b32_e32 v113, v0
	v_mov_b32_e32 v114, v0
	v_mov_b32_e32 v115, v0
	v_mov_b32_e32 v116, v0
	v_mov_b32_e32 v117, v0
	v_mov_b32_e32 v118, v0
	v_mov_b32_e32 v119, v0
	v_mov_b32_e32 v136, v0
	v_mov_b32_e32 v137, v0
	v_mov_b32_e32 v138, v0
	v_mov_b32_e32 v139, v0
	v_mov_b32_e32 v140, v0
	v_mov_b32_e32 v141, v0
	v_mov_b32_e32 v142, v0
	v_mov_b32_e32 v143, v0

.LBB0_1279:
	s_ashr_i32 s15, s14, 31
	s_lshl_b64 s[16:17], s[14:15], 20
	s_add_u32 s16, s51, s16
	s_addc_u32 s17, s52, s17
	s_and_b64 s[18:19], s[4:5], exec
	s_cselect_b32 s1, s17, s23
	s_cselect_b32 s15, s16, s22
	s_ashr_i32 s13, s12, 31
	s_lshl_b64 s[18:19], s[12:13], 20
	s_add_u32 s18, s2, s18
	s_addc_u32 s19, s3, s19
	s_and_b64 s[26:27], s[4:5], exec
	s_cselect_b32 s13, s19, s25
	s_cselect_b32 s44, s18, s24
	s_add_u32 s22, s22, 0x80080
	s_addc_u32 s23, s23, 0
	s_add_u32 s45, s24, 0x100
	v_mov_b32_e32 v0, 0
	s_addc_u32 s46, s25, 0
	s_mov_b32 s47, -2
	s_waitcnt lgkmcnt(0)
	v_mov_b32_e32 v1, v0
	v_mov_b32_e32 v2, v0
	v_mov_b32_e32 v3, v0
	v_mov_b32_e32 v4, v0
	v_mov_b32_e32 v5, v0
	v_mov_b32_e32 v6, v0
	v_mov_b32_e32 v7, v0
	v_mov_b32_e32 v16, v0
	v_mov_b32_e32 v17, v0
	v_mov_b32_e32 v18, v0
	v_mov_b32_e32 v19, v0
	v_mov_b32_e32 v20, v0
	v_mov_b32_e32 v21, v0
	v_mov_b32_e32 v22, v0
	v_mov_b32_e32 v23, v0
	v_mov_b32_e32 v32, v0
	v_mov_b32_e32 v33, v0
	v_mov_b32_e32 v34, v0
	v_mov_b32_e32 v35, v0
	v_mov_b32_e32 v36, v0
	v_mov_b32_e32 v37, v0
	v_mov_b32_e32 v38, v0
	v_mov_b32_e32 v39, v0
	v_mov_b32_e32 v48, v0
	v_mov_b32_e32 v49, v0
	v_mov_b32_e32 v50, v0
	v_mov_b32_e32 v51, v0
	v_mov_b32_e32 v52, v0
	v_mov_b32_e32 v53, v0
	v_mov_b32_e32 v54, v0
	v_mov_b32_e32 v55, v0
	v_mov_b32_e32 v8, v0
	v_mov_b32_e32 v9, v0
	v_mov_b32_e32 v10, v0
	v_mov_b32_e32 v11, v0
	v_mov_b32_e32 v12, v0
	v_mov_b32_e32 v13, v0
	v_mov_b32_e32 v14, v0
	v_mov_b32_e32 v15, v0
	v_mov_b32_e32 v24, v0
	v_mov_b32_e32 v25, v0
	v_mov_b32_e32 v26, v0
	v_mov_b32_e32 v27, v0
	v_mov_b32_e32 v28, v0
	v_mov_b32_e32 v29, v0
	v_mov_b32_e32 v30, v0
	v_mov_b32_e32 v31, v0
	v_mov_b32_e32 v40, v0
	v_mov_b32_e32 v41, v0
	v_mov_b32_e32 v42, v0
	v_mov_b32_e32 v43, v0
	v_mov_b32_e32 v44, v0
	v_mov_b32_e32 v45, v0
	v_mov_b32_e32 v46, v0
	v_mov_b32_e32 v47, v0
	v_mov_b32_e32 v56, v0
	v_mov_b32_e32 v57, v0
	v_mov_b32_e32 v58, v0
	v_mov_b32_e32 v59, v0
	v_mov_b32_e32 v60, v0
	v_mov_b32_e32 v61, v0
	v_mov_b32_e32 v62, v0
	v_mov_b32_e32 v63, v0
	v_mov_b32_e32 v64, v0
	v_mov_b32_e32 v65, v0
	v_mov_b32_e32 v66, v0
	v_mov_b32_e32 v67, v0
	v_mov_b32_e32 v68, v0
	v_mov_b32_e32 v69, v0
	v_mov_b32_e32 v70, v0
	v_mov_b32_e32 v71, v0
	v_mov_b32_e32 v80, v0
	v_mov_b32_e32 v81, v0
	v_mov_b32_e32 v82, v0
	v_mov_b32_e32 v83, v0
	v_mov_b32_e32 v84, v0
	v_mov_b32_e32 v85, v0
	v_mov_b32_e32 v86, v0
	v_mov_b32_e32 v87, v0
	v_mov_b32_e32 v96, v0
	v_mov_b32_e32 v97, v0
	v_mov_b32_e32 v98, v0
	v_mov_b32_e32 v99, v0
	v_mov_b32_e32 v100, v0
	v_mov_b32_e32 v101, v0
	v_mov_b32_e32 v102, v0
	v_mov_b32_e32 v103, v0
	v_mov_b32_e32 v112, v0
	v_mov_b32_e32 v113, v0
	v_mov_b32_e32 v114, v0
	v_mov_b32_e32 v115, v0
	v_mov_b32_e32 v116, v0
	v_mov_b32_e32 v117, v0
	v_mov_b32_e32 v118, v0
	v_mov_b32_e32 v119, v0
	v_mov_b32_e32 v72, v0
	v_mov_b32_e32 v73, v0
	v_mov_b32_e32 v74, v0
	v_mov_b32_e32 v75, v0
	v_mov_b32_e32 v76, v0
	v_mov_b32_e32 v77, v0
	v_mov_b32_e32 v78, v0
	v_mov_b32_e32 v79, v0
	v_mov_b32_e32 v88, v0
	v_mov_b32_e32 v89, v0
	v_mov_b32_e32 v90, v0
	v_mov_b32_e32 v91, v0
	v_mov_b32_e32 v92, v0
	v_mov_b32_e32 v93, v0
	v_mov_b32_e32 v94, v0
	v_mov_b32_e32 v95, v0
	v_mov_b32_e32 v104, v0
	v_mov_b32_e32 v105, v0
	v_mov_b32_e32 v106, v0
	v_mov_b32_e32 v107, v0
	v_mov_b32_e32 v108, v0
	v_mov_b32_e32 v109, v0
	v_mov_b32_e32 v110, v0
	v_mov_b32_e32 v111, v0
	v_mov_b32_e32 v120, v0
	v_mov_b32_e32 v121, v0
	v_mov_b32_e32 v122, v0
	v_mov_b32_e32 v123, v0
	v_mov_b32_e32 v124, v0
	v_mov_b32_e32 v125, v0
	v_mov_b32_e32 v126, v0
	v_mov_b32_e32 v127, v0

.LBB0_1363:
	s_ashr_i32 s17, s16, 31
	s_lshl_b64 s[18:19], s[16:17], 20
	s_add_u32 s18, s72, s18
	s_addc_u32 s19, s73, s19
	s_and_b64 s[20:21], s[4:5], exec
	s_cselect_b32 s17, s19, s7
	s_cselect_b32 s45, s18, s6
	s_ashr_i32 s15, s14, 31
	s_lshl_b64 s[20:21], s[14:15], 20
	s_add_u32 s20, s2, s20
	s_addc_u32 s21, s3, s21
	s_and_b64 s[24:25], s[4:5], exec
	s_cselect_b32 s15, s21, s23
	s_cselect_b32 s46, s20, s22
	s_add_u32 s6, s6, 0x80080
	s_addc_u32 s7, s7, 0
	s_add_u32 s47, s22, 0x100
	v_mov_b32_e32 v0, 0
	s_addc_u32 s48, s23, 0
	s_mov_b32 s49, -2
	v_mov_b32_e32 v1, v0
	v_mov_b32_e32 v2, v0
	v_mov_b32_e32 v3, v0
	v_mov_b32_e32 v8, v0
	v_mov_b32_e32 v9, v0
	v_mov_b32_e32 v10, v0
	v_mov_b32_e32 v11, v0
	v_mov_b32_e32 v16, v0
	v_mov_b32_e32 v17, v0
	v_mov_b32_e32 v18, v0
	v_mov_b32_e32 v19, v0
	v_mov_b32_e32 v24, v0
	v_mov_b32_e32 v25, v0
	v_mov_b32_e32 v26, v0
	v_mov_b32_e32 v27, v0
	v_mov_b32_e32 v32, v0
	v_mov_b32_e32 v33, v0
	v_mov_b32_e32 v34, v0
	v_mov_b32_e32 v35, v0
	v_mov_b32_e32 v40, v0
	v_mov_b32_e32 v41, v0
	v_mov_b32_e32 v42, v0
	v_mov_b32_e32 v43, v0
	v_mov_b32_e32 v48, v0
	v_mov_b32_e32 v49, v0
	v_mov_b32_e32 v50, v0
	v_mov_b32_e32 v51, v0
	v_mov_b32_e32 v56, v0
	v_mov_b32_e32 v57, v0
	v_mov_b32_e32 v58, v0
	v_mov_b32_e32 v59, v0
	v_mov_b32_e32 v4, v0
	v_mov_b32_e32 v5, v0
	v_mov_b32_e32 v6, v0
	v_mov_b32_e32 v7, v0
	v_mov_b32_e32 v12, v0
	v_mov_b32_e32 v13, v0
	v_mov_b32_e32 v14, v0
	v_mov_b32_e32 v15, v0
	v_mov_b32_e32 v20, v0
	v_mov_b32_e32 v21, v0
	v_mov_b32_e32 v22, v0
	v_mov_b32_e32 v23, v0
	v_mov_b32_e32 v28, v0
	v_mov_b32_e32 v29, v0
	v_mov_b32_e32 v30, v0
	v_mov_b32_e32 v31, v0
	v_mov_b32_e32 v36, v0
	v_mov_b32_e32 v37, v0
	v_mov_b32_e32 v38, v0
	v_mov_b32_e32 v39, v0
	v_mov_b32_e32 v44, v0
	v_mov_b32_e32 v45, v0
	v_mov_b32_e32 v46, v0
	v_mov_b32_e32 v47, v0
	v_mov_b32_e32 v52, v0
	v_mov_b32_e32 v53, v0
	v_mov_b32_e32 v54, v0
	v_mov_b32_e32 v55, v0
	v_mov_b32_e32 v60, v0
	v_mov_b32_e32 v61, v0
	v_mov_b32_e32 v62, v0
	v_mov_b32_e32 v63, v0
	v_mov_b32_e32 v64, v0
	v_mov_b32_e32 v65, v0
	v_mov_b32_e32 v66, v0
	v_mov_b32_e32 v67, v0
	v_mov_b32_e32 v72, v0
	v_mov_b32_e32 v73, v0
	v_mov_b32_e32 v74, v0
	v_mov_b32_e32 v75, v0
	v_mov_b32_e32 v80, v0
	v_mov_b32_e32 v81, v0
	v_mov_b32_e32 v82, v0
	v_mov_b32_e32 v83, v0
	v_mov_b32_e32 v88, v0
	v_mov_b32_e32 v89, v0
	v_mov_b32_e32 v90, v0
	v_mov_b32_e32 v91, v0
	v_mov_b32_e32 v96, v0
	v_mov_b32_e32 v97, v0
	v_mov_b32_e32 v98, v0
	v_mov_b32_e32 v99, v0
	v_mov_b32_e32 v104, v0
	v_mov_b32_e32 v105, v0
	v_mov_b32_e32 v106, v0
	v_mov_b32_e32 v107, v0
	v_mov_b32_e32 v112, v0
	v_mov_b32_e32 v113, v0
	v_mov_b32_e32 v114, v0
	v_mov_b32_e32 v115, v0
	v_mov_b32_e32 v120, v0
	v_mov_b32_e32 v121, v0
	v_mov_b32_e32 v122, v0
	v_mov_b32_e32 v123, v0
	v_mov_b32_e32 v68, v0
	v_mov_b32_e32 v69, v0
	v_mov_b32_e32 v70, v0
	v_mov_b32_e32 v71, v0
	v_mov_b32_e32 v76, v0
	v_mov_b32_e32 v77, v0
	v_mov_b32_e32 v78, v0
	v_mov_b32_e32 v79, v0
	v_mov_b32_e32 v84, v0
	v_mov_b32_e32 v85, v0
	v_mov_b32_e32 v86, v0
	v_mov_b32_e32 v87, v0
	v_mov_b32_e32 v92, v0
	v_mov_b32_e32 v93, v0
	v_mov_b32_e32 v94, v0
	v_mov_b32_e32 v95, v0
	v_mov_b32_e32 v100, v0
	v_mov_b32_e32 v101, v0
	v_mov_b32_e32 v102, v0
	v_mov_b32_e32 v103, v0
	v_mov_b32_e32 v108, v0
	v_mov_b32_e32 v109, v0
	v_mov_b32_e32 v110, v0
	v_mov_b32_e32 v111, v0
	v_mov_b32_e32 v116, v0
	v_mov_b32_e32 v117, v0
	v_mov_b32_e32 v118, v0
	v_mov_b32_e32 v119, v0
	v_mov_b32_e32 v124, v0
	v_mov_b32_e32 v125, v0
	v_mov_b32_e32 v126, v0
	v_mov_b32_e32 v127, v0
